# v114 + prompt-first workgroups take their first conv item statically (queue index 128 + rank), dynamic queue starts at 256
# speedup vs baseline: 1.0050x; 1.0017x over previous
; __device__ __forceinline__ void p_mixer(const Args& a, int l, LAS unsigned char* lds, int tid, int lane, int wave, int bid, int G) {
;     ...
;         if (!prompt_done && (!qfirst || pulled >= 1 || queue_empty)) {
; #pragma unroll 1
;             for (int it = bid; it < N_AP; it += G) { asm volatile("" : "+v"(tid)); lane = tid & 63; attn_prompt_item(a, l, it, lds, tid, lane, wave); }
;             prompt_done = true; continue;
;         }
;         if (queue_empty) break;
;         if (threadIdx.x == 0) slot[0] = __hip_atomic_fetch_add(head, 1u, __ATOMIC_RELAXED, __HIP_MEMORY_SCOPE_AGENT);
;         __syncthreads();
;         const int q = (int)slot[0];
;         __syncthreads();
;         if (q >= N_AS + N_CV) { queue_empty = true; continue; }
;         ++pulled;
;         asm volatile("" : "+v"(tid)); lane = tid & 63;
;         if (q < N_AS) attn_sample_item(a, l, q, lds, tid, lane, wave);
;         else conv_item(a, l, q - N_AS, lane, wave);
.Lq_stat_conv:
	s_lshr_b32 s6, s71, 4
	s_lshl_b32 s6, s6, 3
	s_and_b32 s7, s71, 7
	s_or_b32 s6, s6, s7
	s_addk_i32 s6, 0x80
	v_mov_b32_e32 v1, s6
	s_branch .LBB0_450
.Lq_dyn128:
	global_atomic_add v1, v173, v1, s[2:3] sc0
	s_waitcnt vmcnt(0)
	v_add_u32_e32 v1, 0x100, v1
	s_branch .LBB0_450
